# plus NSA: epilogue gate loads hoisted before tile loop; compressed K/V staging loads all issued up front
# speedup vs baseline: 1.0106x; 1.0106x over previous
.LBB0_676:
	s_or_b64 exec, exec, s[0:1]
	v_readlane_b32 s0, v253, 5
	s_waitcnt lgkmcnt(0)
	s_barrier
	s_waitcnt vmcnt(7)
	v_mov_b32_e32 v1, s0
	ds_read_b32 v1, v1
	s_waitcnt lgkmcnt(0)
	s_barrier
	v_cmp_lt_i32_e64 s[0:1], s40, v1
	v_readfirstlane_b32 s3, v1
	s_and_b64 vcc, exec, s[0:1]
	s_cbranch_vccnz .LBB0_671
	v_writelane_b32 v254, s0, 21
	s_cmp_gt_i32 s3, 63
	s_nop 0
	v_writelane_b32 v254, s1, 22
	s_mov_b64 s[0:1], -1
	s_cbranch_scc0 .LBB0_854
	s_sub_i32 s0, s3, 64
	s_lshl_b32 s1, s3, 5
	s_and_b32 s1, s1, 0x1e0
	s_lshr_b32 s0, s0, 4
	s_sub_i32 s0, s1, s0
	s_add_i32 s0, s0, 31
	v_mov_b32_e32 v1, v182
	s_and_b32 s78, s0, 31
	v_and_b32_e32 v66, 31, v1
	s_waitcnt vmcnt(2)
	v_lshrrev_b32_e32 v15, 1, v1
	s_lshl_b32 s2, s78, 6
	v_and_or_b32 v68, v15, 32, v66
	s_lshr_b32 s88, s0, 5
	v_ashrrev_i32_e32 v71, 7, v1
	v_or_b32_e32 v67, s2, v68
	v_lshl_or_b32 v108, s88, 11, v67
	v_mov_b64_e32 v[2:3], s[58:59]
	s_movk_i32 s0, 0x1e00
	s_waitcnt vmcnt(0)
	v_lshlrev_b32_e32 v112, 6, v71
	v_bfe_u32 v69, v1, 5, 1
	v_mad_u64_u32 v[110:111], s[0:1], v108, s0, v[2:3]
	v_ashrrev_i32_e32 v113, 31, v112
	v_lshl_add_u64 v[2:3], v[112:113], 1, v[110:111]
	v_lshlrev_b32_e32 v4, 4, v69
	v_mov_b32_e32 v5, v0
	v_lshl_add_u64 v[2:3], v[2:3], 0, v[4:5]
	s_mov_b64 s[0:1], 0x1700
	v_mov_b32_e32 v109, v0
	v_lshl_add_u64 v[4:5], v[2:3], 0, s[0:1]
	v_add_co_u32_e32 v2, vcc, s86, v2
	s_addk_i32 s2, 0x220
	s_nop 0
	v_addc_co_u32_e32 v3, vcc, 0, v3, vcc
	global_load_dwordx4 v[80:83], v[4:5], off offset:32
	global_load_dwordx4 v[84:87], v[4:5], off offset:64
	global_load_dwordx4 v[88:91], v[2:3], off offset:1792
	global_load_dwordx4 v[92:95], v[4:5], off offset:96
	v_lshl_add_u32 v2, v71, 1, v71
	v_lshlrev_b64 v[4:5], 7, v[108:109]
	v_ashrrev_i32_e32 v3, 31, v2
	v_lshl_add_u64 v[4:5], s[60:61], 0, v[4:5]
	v_lshl_add_u64 v[2:3], v[2:3], 2, v[4:5]
	global_load_dwordx3 v[104:106], v[2:3], off offset:32
	s_and_b32 s6, s2, 0xe00
	v_writelane_b32 v254, s3, 23
	v_cmp_gt_i32_e32 vcc, s6, v1
	s_and_saveexec_b64 s[0:1], vcc
	s_cbranch_execz .LBB0_683
	s_lshl_b32 s2, s78, 2
	s_or_b32 s7, s2, 3
	s_lshl_b32 s2, s88, 15
	s_add_u32 s2, s66, s2
	v_and_b32_e32 v6, 15, v1
	s_addc_u32 s3, s67, 0
	s_lshl_b64 s[4:5], s[88:89], 15
	v_lshlrev_b32_e32 v2, 4, v6
	v_mov_b32_e32 v3, v0
	s_add_u32 s4, s66, s4
	v_lshl_add_u64 v[4:5], s[2:3], 0, v[2:3]
	s_mov_b64 s[2:3], 0x80000
	s_addc_u32 s5, s67, s5
	v_lshl_add_u64 v[10:11], v[4:5], 0, s[2:3]
	v_readlane_b32 s2, v253, 20
	v_lshl_add_u64 v[12:13], s[4:5], 0, v[2:3]
	v_lshl_add_u32 v14, v6, 3, 0
	v_mov_b32_e32 v2, s2
	s_movk_i32 s2, 0x420
	s_waitcnt vmcnt(6)
	v_mad_u32_u24 v16, v6, s2, v2
	s_mov_b64 s[2:3], 0
	v_mov_b32_e32 v17, v1
	v_ashrrev_i32_e32 v244, 4, v17
	s_lshr_b32 s98, s6, 9
	v_mov_b32_e32 v247, 0
	v_mov_b32_e32 v206, 0
	v_mov_b32_e32 v207, 0
	v_mov_b32_e32 v208, 0
	v_mov_b32_e32 v209, 0
	v_mov_b32_e32 v210, 0
	v_mov_b32_e32 v211, 0
	v_mov_b32_e32 v212, 0
	v_mov_b32_e32 v213, 0
	v_mov_b32_e32 v214, 0
	v_mov_b32_e32 v215, 0
	v_mov_b32_e32 v216, 0
	v_mov_b32_e32 v217, 0
	v_mov_b32_e32 v218, 0
	v_mov_b32_e32 v219, 0
	v_mov_b32_e32 v220, 0
	v_mov_b32_e32 v221, 0
	v_mov_b32_e32 v222, 0
	v_mov_b32_e32 v223, 0
	v_mov_b32_e32 v224, 0
	v_mov_b32_e32 v225, 0
	v_mov_b32_e32 v226, 0
	v_mov_b32_e32 v227, 0
	v_mov_b32_e32 v228, 0
	v_mov_b32_e32 v229, 0
	v_mov_b32_e32 v230, 0
	v_mov_b32_e32 v231, 0
	v_mov_b32_e32 v232, 0
	v_mov_b32_e32 v233, 0
	v_mov_b32_e32 v234, 0
	v_mov_b32_e32 v235, 0
	v_mov_b32_e32 v236, 0
	v_mov_b32_e32 v237, 0
	v_add_u32_e32 v245, 0, v244
	v_cmp_gt_i32_e32 vcc, s7, v245
	s_and_saveexec_b64 s[4:5], vcc
	v_lshlrev_b32_e32 v246, 8, v245
	v_lshl_add_u64 v[248:249], v[12:13], 0, v[246:247]
	global_load_dwordx4 v[206:209], v[248:249], off
	v_lshl_add_u64 v[248:249], v[10:11], 0, v[246:247]
	global_load_dwordx4 v[210:213], v[248:249], off
	s_or_b64 exec, exec, s[4:5]
	s_cmp_lt_u32 s98, 2
	s_cbranch_scc1 .Lkc_pf_done
	v_add_u32_e32 v245, 32, v244
	v_cmp_gt_i32_e32 vcc, s7, v245
	s_and_saveexec_b64 s[4:5], vcc
	v_lshlrev_b32_e32 v246, 8, v245
	v_lshl_add_u64 v[248:249], v[12:13], 0, v[246:247]
	global_load_dwordx4 v[214:217], v[248:249], off
	v_lshl_add_u64 v[248:249], v[10:11], 0, v[246:247]
	global_load_dwordx4 v[218:221], v[248:249], off
	s_or_b64 exec, exec, s[4:5]
	s_cmp_lt_u32 s98, 3
	s_cbranch_scc1 .Lkc_pf_done
	v_add_u32_e32 v245, 64, v244
	v_cmp_gt_i32_e32 vcc, s7, v245
	s_and_saveexec_b64 s[4:5], vcc
	v_lshlrev_b32_e32 v246, 8, v245
	v_lshl_add_u64 v[248:249], v[12:13], 0, v[246:247]
	global_load_dwordx4 v[222:225], v[248:249], off
	v_lshl_add_u64 v[248:249], v[10:11], 0, v[246:247]
	global_load_dwordx4 v[226:229], v[248:249], off
	s_or_b64 exec, exec, s[4:5]
	s_cmp_lt_u32 s98, 4
	s_cbranch_scc1 .Lkc_pf_done
	v_add_u32_e32 v245, 96, v244
	v_cmp_gt_i32_e32 vcc, s7, v245
	s_and_saveexec_b64 s[4:5], vcc
	v_lshlrev_b32_e32 v246, 8, v245
	v_lshl_add_u64 v[248:249], v[12:13], 0, v[246:247]
	global_load_dwordx4 v[230:233], v[248:249], off
	v_lshl_add_u64 v[248:249], v[10:11], 0, v[246:247]
	global_load_dwordx4 v[234:237], v[248:249], off
	s_or_b64 exec, exec, s[4:5]
.Lkc_pf_done:
	s_mov_b32 s99, 0
	s_branch .LBB0_681
.LBB0_680:
	s_or_b64 exec, exec, s[4:5]
	s_nop 0
	v_and_b32_sdwa v19, v7, v190 dst_sel:DWORD dst_unused:UNUSED_PAD src0_sel:WORD_1 src1_sel:DWORD
	v_and_b32_sdwa v20, v6, v190 dst_sel:DWORD dst_unused:UNUSED_PAD src0_sel:WORD_1 src1_sel:DWORD
	v_add3_u32 v19, v7, v19, s39
	v_add3_u32 v22, v6, v20, s39
	v_and_b32_e32 v21, 0xffff0000, v19
	v_and_b32_e32 v20, 0xffff0000, v22
	v_pk_add_f32 v[6:7], v[6:7], v[20:21] neg_lo:[0,1] neg_hi:[0,1]
	v_and_b32_sdwa v19, v8, v190 dst_sel:DWORD dst_unused:UNUSED_PAD src0_sel:WORD_1 src1_sel:DWORD
	v_cvt_pk_bf16_f32 v6, v6, v7
	v_and_b32_sdwa v7, v9, v190 dst_sel:DWORD dst_unused:UNUSED_PAD src0_sel:WORD_1 src1_sel:DWORD
	v_add3_u32 v7, v9, v7, s39
	v_add3_u32 v19, v8, v19, s39
	v_or_b32_sdwa v22, v21, v22 dst_sel:DWORD dst_unused:UNUSED_PAD src0_sel:DWORD src1_sel:WORD_1
	v_and_b32_e32 v21, 0xffff0000, v7
	v_and_b32_e32 v20, 0xffff0000, v19
	v_pk_add_f32 v[8:9], v[8:9], v[20:21] neg_lo:[0,1] neg_hi:[0,1]
	s_movk_i32 s4, 0x90
	v_or_b32_sdwa v23, v21, v19 dst_sel:DWORD dst_unused:UNUSED_PAD src0_sel:DWORD src1_sel:WORD_1
	v_cvt_pk_bf16_f32 v7, v8, v9
	v_mad_u64_u32 v[8:9], s[4:5], v18, s4, v[14:15]
	ds_write2st64_b64 v8, v[22:23], v[6:7] offset0:70 offset1:106
	s_nop 0
	v_bfe_u32 v6, v2, 16, 1
	v_add3_u32 v2, v2, v6, s39
	v_lshl_add_u32 v6, v18, 1, v16
	ds_write_b16_d16_hi v6, v2
	v_bfe_u32 v2, v3, 16, 1
	v_add3_u32 v2, v3, v2, s39
	ds_write_b16_d16_hi v6, v2 offset:264
	v_bfe_u32 v2, v4, 16, 1
	v_add3_u32 v2, v4, v2, s39
	v_add_u32_e32 v17, 0x200, v17
	ds_write_b16_d16_hi v6, v2 offset:528
	v_bfe_u32 v2, v5, 16, 1
	v_cmp_le_i32_e32 vcc, s6, v17
	v_add3_u32 v2, v5, v2, s39
	s_or_b64 s[2:3], vcc, s[2:3]
	ds_write_b16_d16_hi v6, v2 offset:792
	s_andn2_b64 exec, exec, s[2:3]
	s_cbranch_execz .LBB0_683
.LBB0_681:
	v_ashrrev_i32_e32 v18, 4, v17
	s_sub_i32 s4, s98, s99
	s_cmp_eq_u32 s4, 1
	s_cbranch_scc1 .Lkc_w0
	s_cmp_eq_u32 s4, 2
	s_cbranch_scc1 .Lkc_w2
	s_cmp_eq_u32 s4, 3
	s_cbranch_scc1 .Lkc_w4
	s_waitcnt vmcnt(6)
	s_branch .Lkc_wd
.Lkc_w4:
	s_waitcnt vmcnt(4)
	s_branch .Lkc_wd
.Lkc_w2:
	s_waitcnt vmcnt(2)
	s_branch .Lkc_wd
.Lkc_w0:
	s_waitcnt vmcnt(0)
.Lkc_wd:
	s_cmp_eq_u32 s99, 1
	s_cbranch_scc1 .Lkc_c1
	s_cmp_eq_u32 s99, 2
	s_cbranch_scc1 .Lkc_c2
	s_cmp_eq_u32 s99, 3
	s_cbranch_scc1 .Lkc_c3
	v_mov_b32_e32 v6, v206
	v_mov_b32_e32 v7, v207
	v_mov_b32_e32 v8, v208
	v_mov_b32_e32 v9, v209
	v_mov_b32_e32 v2, v210
	v_mov_b32_e32 v3, v211
	v_mov_b32_e32 v4, v212
	v_mov_b32_e32 v5, v213
	s_branch .Lkc_cd
.Lkc_c1:
	v_mov_b32_e32 v6, v214
	v_mov_b32_e32 v7, v215
	v_mov_b32_e32 v8, v216
	v_mov_b32_e32 v9, v217
	v_mov_b32_e32 v2, v218
	v_mov_b32_e32 v3, v219
	v_mov_b32_e32 v4, v220
	v_mov_b32_e32 v5, v221
	s_branch .Lkc_cd
.Lkc_c2:
	v_mov_b32_e32 v6, v222
	v_mov_b32_e32 v7, v223
	v_mov_b32_e32 v8, v224
	v_mov_b32_e32 v9, v225
	v_mov_b32_e32 v2, v226
	v_mov_b32_e32 v3, v227
	v_mov_b32_e32 v4, v228
	v_mov_b32_e32 v5, v229
	s_branch .Lkc_cd
.Lkc_c3:
	v_mov_b32_e32 v6, v230
	v_mov_b32_e32 v7, v231
	v_mov_b32_e32 v8, v232
	v_mov_b32_e32 v9, v233
	v_mov_b32_e32 v2, v234
	v_mov_b32_e32 v3, v235
	v_mov_b32_e32 v4, v236
	v_mov_b32_e32 v5, v237
.Lkc_cd:
	s_add_i32 s99, s99, 1
	s_mov_b64 s[4:5], exec
	s_branch .LBB0_680

.LBB0_733:
	s_or_b64 exec, exec, s[4:5]
	s_add_i32 s74, 0, 0x1e310
	v_mul_f32_e32 v36, v1, v40
	v_mov_b32_e32 v1, s74
	s_waitcnt lgkmcnt(0)
	s_barrier
	ds_read_b32 v1, v1
	s_sub_i32 s0, s78, s2
	s_add_i32 s73, s0, s81
	s_add_i32 s73, s73, 1
	s_movk_i32 s0, 0x200
	s_waitcnt lgkmcnt(0)
	v_readfirstlane_b32 s2, v1
	s_bitcmp0_b32 s2, 8
	s_cselect_b32 s68, 0x100, s0
	s_lshl_b64 s[0:1], s[88:89], 11
	s_lshl_b32 s2, s2, 6
	v_ashrrev_i32_e32 v35, 31, v34
	s_and_b32 s88, s2, 0x3fc0
	v_lshl_add_u64 v[146:147], s[0:1], 0, v[34:35]
	v_readlane_b32 s0, v253, 32
	v_readlane_b32 s2, v253, 34
	v_readlane_b32 s3, v253, 35
	v_pk_mul_f32 v[142:143], v[36:37], v[4:5] op_sel_hi:[0,1]
	v_pk_mul_f32 v[144:145], v[36:37], v[2:3] op_sel_hi:[0,1]
	v_lshl_add_u64 v[2:3], v[146:147], 0, s[88:89]
	v_readlane_b32 s1, v253, 33
	v_mov_b64_e32 v[4:5], s[2:3]
	s_movk_i32 s2, 0x1e00
	v_mad_u64_u32 v[4:5], s[0:1], v2, s2, v[4:5]
	s_mov_b32 s69, 0
	v_mad_i32_i24 v5, v3, s2, v5
	v_lshl_add_u64 v[2:3], v[4:5], 0, s[68:69]
	v_lshlrev_b32_e32 v4, 4, v39
	v_mov_b32_e32 v5, v0
	v_lshl_add_u64 v[2:3], v[2:3], 0, v[4:5]
	s_mov_b64 s[0:1], 0x1900
	v_pk_mul_f32 v[140:141], v[36:37], v[6:7] op_sel_hi:[0,1]
	v_lshl_add_u64 v[6:7], v[2:3], 0, s[0:1]
	v_add_co_u32_e32 v2, vcc, s86, v2
	s_movk_i32 s0, 0x90
	s_nop 0
	v_addc_co_u32_e32 v3, vcc, 0, v3, vcc
	global_load_dwordx4 v[96:99], v[2:3], off offset:2304
	global_load_dwordx4 v[100:103], v[6:7], off offset:128
	v_mul_lo_u32 v1, v34, s0
	s_movk_i32 s0, 0xff72
	v_add_u32_e32 v1, 0, v1
	v_mul_lo_u32 v2, v34, s0
	v_mul_u32_u24_e32 v3, 0x440, v39
	v_pk_mul_f32 v[130:131], v[36:37], v[16:17] op_sel_hi:[0,1]
	v_pk_mul_f32 v[132:133], v[36:37], v[14:15] op_sel_hi:[0,1]
	v_pk_mul_f32 v[134:135], v[36:37], v[12:13] op_sel_hi:[0,1]
	v_pk_mul_f32 v[136:137], v[36:37], v[10:11] op_sel_hi:[0,1]
	v_pk_mul_f32 v[138:139], v[36:37], v[8:9] op_sel_hi:[0,1]
	v_pk_mul_f32 v[114:115], v[36:37], v[32:33] op_sel_hi:[0,1]
	v_pk_mul_f32 v[116:117], v[36:37], v[30:31] op_sel_hi:[0,1]
	v_pk_mul_f32 v[118:119], v[36:37], v[28:29] op_sel_hi:[0,1]
	v_pk_mul_f32 v[120:121], v[36:37], v[26:27] op_sel_hi:[0,1]
	v_pk_mul_f32 v[122:123], v[36:37], v[24:25] op_sel_hi:[0,1]
	v_pk_mul_f32 v[124:125], v[36:37], v[22:23] op_sel_hi:[0,1]
	v_pk_mul_f32 v[126:127], v[36:37], v[20:21] op_sel_hi:[0,1]
	v_pk_mul_f32 v[128:129], v[36:37], v[18:19] op_sel_hi:[0,1]
	v_add_u32_e32 v153, v1, v4
	v_add3_u32 v154, v1, v2, v3
	s_cmp_lt_i32 s73, 1
	v_readlane_b32 s4, v253, 36
	v_readlane_b32 s5, v253, 37
	v_readlane_b32 s6, v253, 38
	v_readlane_b32 s7, v253, 39
	v_readlane_b32 s8, v253, 40
	v_readlane_b32 s9, v253, 41
	v_readlane_b32 s10, v253, 42
	v_readlane_b32 s11, v253, 43
	v_readlane_b32 s12, v253, 44
	v_readlane_b32 s13, v253, 45
	v_readlane_b32 s14, v253, 46
	v_readlane_b32 s15, v253, 47
	s_waitcnt vmcnt(1)
	ds_write_b128 v153, v[96:99]
	s_waitcnt vmcnt(0)
	ds_write_b16 v154, v100 offset:18432
	ds_write_b16_d16_hi v154, v100 offset:18568
	ds_write_b16 v154, v101 offset:18704
	ds_write_b16_d16_hi v154, v101 offset:18840
	ds_write_b16 v154, v102 offset:18976
	ds_write_b16_d16_hi v154, v102 offset:19112
	ds_write_b16 v154, v103 offset:19248
	ds_write_b16_d16_hi v154, v103 offset:19384
	v_lshlrev_b64 v[238:239], 1, v[112:113]
	v_lshl_add_u64 v[240:241], v[110:111], 0, v[238:239]
	v_lshlrev_b32_e32 v238, 1, v150
	v_mov_b32_e32 v239, v0
	v_lshl_add_u64 v[240:241], v[240:241], 0, v[238:239]
	v_add_co_u32_e32 v238, vcc, s86, v240
	s_mov_b64 s[0:1], 0x1c00
	s_nop 1
	v_addc_co_u32_e32 v239, vcc, 0, v241, vcc
	v_lshl_add_u64 v[242:243], v[240:241], 0, s[0:1]
	global_load_dwordx2 v[222:223], v[238:239], off offset:3072
	global_load_dwordx2 v[224:225], v[242:243], off offset:16
	global_load_dwordx2 v[226:227], v[242:243], off offset:32
	global_load_dwordx2 v[228:229], v[242:243], off offset:48
	global_load_dwordx2 v[230:231], v[242:243], off offset:64
	global_load_dwordx2 v[232:233], v[242:243], off offset:80
	global_load_dwordx2 v[234:235], v[242:243], off offset:96
	global_load_dwordx2 v[236:237], v[242:243], off offset:112
	s_waitcnt lgkmcnt(0)
	s_barrier
	s_cbranch_scc1 .LBB0_852
	v_mul_f32_e32 v1, 0xbfb8aa3b, v105
	v_exp_f32_e32 v1, v1
	v_sub_u32_e32 v2, v68, v150
	v_writelane_b32 v254, s41, 25
	v_cmp_gt_i32_e64 s[0:1], 0, v2
	v_add_f32_e32 v1, 1.0, v1
	v_cmp_gt_i32_e64 s[2:3], 35, v2
	v_writelane_b32 v254, s0, 15
	v_rcp_f32_e32 v156, v1
	v_mov_b32_e32 v14, v0
	v_writelane_b32 v254, s1, 16
	v_writelane_b32 v254, s2, 17
	v_mov_b32_e32 v15, v0
	v_lshlrev_b32_e32 v16, 3, v39
	v_writelane_b32 v254, s3, 18
	v_cmp_gt_i32_e64 s[2:3], 8, v2
	v_sub_u32_e32 v155, v150, v67
	v_cmp_gt_i32_e64 s[86:87], 32, v2
	v_cmp_gt_i32_e64 s[94:95], 1, v2
	v_cmp_gt_i32_e64 s[82:83], 33, v2
	v_cmp_gt_i32_e64 s[92:93], 2, v2
	v_cmp_gt_i32_e64 s[96:97], 34, v2
	v_cmp_gt_i32_e64 s[0:1], 3, v2
	v_writelane_b32 v254, s2, 19
	v_cmp_gt_i32_e64 s[20:21], 40, v2
	v_cmp_gt_i32_e64 s[22:23], 9, v2
	v_cmp_gt_i32_e64 s[24:25], 41, v2
	v_cmp_gt_i32_e64 s[26:27], 10, v2
	v_cmp_gt_i32_e64 s[28:29], 42, v2
	v_cmp_gt_i32_e64 s[30:31], 11, v2
	v_cmp_gt_i32_e64 s[34:35], 43, v2
	v_cmp_gt_i32_e64 s[36:37], 16, v2
	v_cmp_gt_i32_e64 s[38:39], 48, v2
	v_cmp_gt_i32_e64 s[40:41], 17, v2
	v_cmp_gt_i32_e64 s[42:43], 49, v2
	v_cmp_gt_i32_e64 s[44:45], 18, v2
	v_cmp_gt_i32_e64 s[46:47], 50, v2
	v_cmp_gt_i32_e64 s[48:49], 19, v2
	v_cmp_gt_i32_e64 s[50:51], 51, v2
	v_cmp_gt_i32_e64 s[52:53], 24, v2
	v_cmp_gt_i32_e64 s[54:55], 56, v2
	v_cmp_gt_i32_e64 s[56:57], 25, v2
	v_cmp_gt_i32_e64 s[58:59], 57, v2
	v_cmp_gt_i32_e64 s[60:61], 26, v2
	v_cmp_gt_i32_e64 s[62:63], 58, v2
	v_cmp_gt_i32_e64 s[64:65], 27, v2
	v_cmp_gt_i32_e64 s[66:67], 59, v2
	v_mul_u32_u24_e32 v158, 0x88, v66
	v_mov_b32_e32 v1, v0
	v_mov_b32_e32 v2, v0
	v_mov_b32_e32 v3, v0
	v_mov_b32_e32 v4, v0
	v_mov_b32_e32 v5, v0
	v_mov_b32_e32 v6, v0
	v_mov_b32_e32 v7, v0
	v_mov_b32_e32 v8, v0
	v_mov_b32_e32 v9, v0
	v_mov_b32_e32 v10, v0
	v_mov_b32_e32 v11, v0
	v_mov_b32_e32 v12, v0
	v_mov_b32_e32 v13, v0
	v_mov_b64_e32 v[78:79], v[14:15]
	v_mov_b64_e32 v[62:63], v[14:15]
	v_mul_u32_u24_e32 v157, 0x90, v37
	v_writelane_b32 v254, s3, 20
	v_mul_u32_u24_e32 v159, 0x88, v37
	v_mov_b32_e32 v161, 0xf149f2ca
	v_mov_b32_e32 v166, 0
	v_lshlrev_b32_e32 v104, 1, v16
	v_mov_b64_e32 v[76:77], v[12:13]
	v_mov_b64_e32 v[74:75], v[10:11]
	v_mov_b64_e32 v[72:73], v[8:9]
	v_mov_b64_e32 v[70:71], v[6:7]
	v_mov_b64_e32 v[68:69], v[4:5]
	v_mov_b64_e32 v[66:67], v[2:3]
	v_mov_b64_e32 v[64:65], v[0:1]
	v_mov_b64_e32 v[60:61], v[12:13]
	v_mov_b64_e32 v[58:59], v[10:11]
	v_mov_b64_e32 v[56:57], v[8:9]
	v_mov_b64_e32 v[54:55], v[6:7]
	v_mov_b64_e32 v[52:53], v[4:5]
	v_mov_b64_e32 v[50:51], v[2:3]
	v_mov_b64_e32 v[48:49], v[0:1]
	s_cmp_lt_i32 s73, 2
	s_cbranch_scc1 .Lnsa_pf_skip
	v_mov_b32_e32 v1, s74
	ds_read_b32 v1, v1 offset:4
	s_movk_i32 s4, 0x200
	s_mov_b32 s91, s89
	v_readlane_b32 s6, v253, 34
	s_waitcnt lgkmcnt(0)
	v_readfirstlane_b32 s68, v1
	s_bitcmp0_b32 s68, 8
	s_cselect_b32 s88, 0x100, s4
	s_lshl_b32 s68, s68, 6
	v_readlane_b32 s7, v253, 35
	s_and_b32 s90, s68, 0x3fc0
	v_lshl_add_u64 v[4:5], v[146:147], 0, s[90:91]
	v_mov_b64_e32 v[2:3], s[6:7]
	s_movk_i32 s4, 0x1e00
	v_mad_u64_u32 v[2:3], s[90:91], v4, s4, v[2:3]
	v_mad_i32_i24 v3, v5, s4, v3
	v_lshl_add_u64 v[2:3], v[2:3], 0, s[88:89]
	v_mov_b32_e32 v105, v0
	v_lshl_add_u64 v[2:3], v[2:3], 0, v[104:105]
	s_mov_b64 s[4:5], 0x1900
	v_lshl_add_u64 v[4:5], v[2:3], 0, s[4:5]
	v_add_co_u32_e32 v2, vcc, 0x1000, v2
	s_nop 1
	v_addc_co_u32_e32 v3, vcc, 0, v3, vcc
	global_load_dwordx4 v[206:209], v[2:3], off offset:2304
	global_load_dwordx4 v[210:213], v[4:5], off offset:128

.LBB0_853:
	v_mov_b32_e32 v2, v166
	s_nop 1
	v_permlane32_swap_b32_e32 v166, v2
	v_add_f32_e32 v2, v166, v2
	v_cmp_lt_f32_e32 vcc, 0, v2
	v_rcp_f32_e32 v2, v2
	v_readlane_b32 s56, v253, 32
	v_lshlrev_b64 v[4:5], 1, v[112:113]
	v_readlane_b32 s62, v253, 38
	v_readlane_b32 s63, v253, 39
	v_lshl_add_u64 v[6:7], v[110:111], 0, v[4:5]
	v_lshlrev_b32_e32 v20, 1, v150
	v_mov_b32_e32 v21, v0
	v_lshlrev_b64 v[8:9], 11, v[108:109]
	v_lshl_add_u64 v[6:7], v[6:7], 0, v[20:21]
	v_lshl_add_u64 v[8:9], s[62:63], 0, v[8:9]
	v_cndmask_b32_e32 v2, 0, v2, vcc
	v_lshl_add_u64 v[24:25], v[8:9], 0, v[4:5]
	v_add_co_u32_e32 v4, vcc, s86, v6
	s_mov_b64 s[0:1], 0x1c00
	s_nop 0
	v_addc_co_u32_e32 v5, vcc, 0, v7, vcc
	v_lshl_add_u64 v[22:23], v[6:7], 0, s[0:1]
	s_waitcnt vmcnt(0)
	v_mov_b32_e32 v26, v222
	v_mov_b32_e32 v27, v223
	v_mov_b32_e32 v18, v224
	v_mov_b32_e32 v19, v225
	v_mov_b32_e32 v16, v226
	v_mov_b32_e32 v17, v227
	v_mov_b32_e32 v14, v228
	v_mov_b32_e32 v15, v229
	v_mov_b32_e32 v12, v230
	v_mov_b32_e32 v13, v231
	v_mov_b32_e32 v10, v232
	v_mov_b32_e32 v11, v233
	v_mov_b32_e32 v8, v234
	v_mov_b32_e32 v9, v235
	v_mov_b32_e32 v4, v236
	v_mov_b32_e32 v5, v237
	v_mul_f32_e32 v1, 0xbfb8aa3b, v106
	v_exp_f32_e32 v1, v1
	v_lshl_add_u64 v[6:7], v[24:25], 0, v[20:21]
	v_readlane_b32 s92, v253, 51
	v_readlane_b32 s3, v254, 23
	v_add_f32_e32 v1, 1.0, v1
	v_rcp_f32_e32 v1, v1
	v_readlane_b32 s73, v253, 49
	v_readlane_b32 s58, v253, 34
	v_readlane_b32 s59, v253, 35
	v_mul_f32_e32 v2, v1, v2
	v_pk_fma_f32 v[20:21], v[64:65], v[2:3], v[144:145] op_sel_hi:[1,0,1]
	v_readlane_b32 s60, v253, 36
	v_readlane_b32 s61, v253, 37
	v_readlane_b32 s66, v253, 42
	v_readlane_b32 s67, v253, 43
	v_readlane_b32 s70, v253, 46
	v_readlane_b32 s71, v253, 47
	v_readlane_b32 s76, v253, 50
	v_readlane_b32 s93, v253, 52
	v_readlane_b32 s81, v253, 53
	v_readlane_b32 s84, v253, 54
	s_movk_i32 s97, 0x2000
	s_movk_i32 s38, 0x480
	s_movk_i32 s39, 0x7fff
	s_movk_i32 s40, 0x23f
	s_mov_b64 s[0:1], 0
	v_readlane_b32 s57, v253, 33
	v_readlane_b32 s64, v253, 40
	v_readlane_b32 s65, v253, 41
	v_readlane_b32 s68, v253, 44
	v_readlane_b32 s69, v253, 45
	s_waitcnt vmcnt(7)
	v_lshlrev_b32_e32 v22, 16, v26
	v_mul_f32_e32 v1, 0xbfb8aa3b, v22
	v_exp_f32_e32 v1, v1
	v_and_b32_e32 v23, 0xffff0000, v26
	v_add_f32_e32 v1, 1.0, v1
	v_rcp_f32_e32 v24, v1
	v_mul_f32_e32 v1, 0xbfb8aa3b, v23
	v_exp_f32_e32 v1, v1
	s_nop 0
	v_add_f32_e32 v1, 1.0, v1
	v_rcp_f32_e32 v25, v1
	s_nop 0
	v_pk_mul_f32 v[22:23], v[24:25], v[22:23]
	v_lshlrev_b32_e32 v24, 16, v27
	v_mul_f32_e32 v1, 0xbfb8aa3b, v24
	v_exp_f32_e32 v1, v1
	v_and_b32_e32 v25, 0xffff0000, v27
	v_pk_mul_f32 v[20:21], v[20:21], v[22:23]
	v_pk_fma_f32 v[22:23], v[66:67], v[2:3], v[142:143] op_sel_hi:[1,0,1]
	v_add_f32_e32 v1, 1.0, v1
	v_rcp_f32_e32 v26, v1
	v_mul_f32_e32 v1, 0xbfb8aa3b, v25
	v_exp_f32_e32 v1, v1
	v_cvt_pk_bf16_f32 v20, v20, v21
	v_add_f32_e32 v1, 1.0, v1
	v_rcp_f32_e32 v27, v1
	s_nop 0
	v_pk_mul_f32 v[24:25], v[26:27], v[24:25]
	s_nop 0
	v_pk_mul_f32 v[22:23], v[22:23], v[24:25]
	s_nop 0
	v_cvt_pk_bf16_f32 v21, v22, v23
	s_waitcnt vmcnt(6)
	v_lshlrev_b32_e32 v22, 16, v18
	v_mul_f32_e32 v1, 0xbfb8aa3b, v22
	v_exp_f32_e32 v1, v1
	v_and_b32_e32 v23, 0xffff0000, v18
	v_lshlrev_b32_e32 v18, 16, v19
	v_and_b32_e32 v19, 0xffff0000, v19
	v_add_f32_e32 v1, 1.0, v1
	v_rcp_f32_e32 v24, v1
	v_mul_f32_e32 v1, 0xbfb8aa3b, v23
	v_exp_f32_e32 v1, v1
	global_store_dwordx2 v[6:7], v[20:21], off offset:1536
	v_pk_fma_f32 v[20:21], v[68:69], v[2:3], v[140:141] op_sel_hi:[1,0,1]
	v_add_f32_e32 v1, 1.0, v1
	v_rcp_f32_e32 v25, v1
	v_mul_f32_e32 v1, 0xbfb8aa3b, v18
	v_exp_f32_e32 v1, v1
	v_pk_mul_f32 v[22:23], v[24:25], v[22:23]
	s_nop 0
	v_pk_mul_f32 v[20:21], v[20:21], v[22:23]
	v_add_f32_e32 v1, 1.0, v1
	v_rcp_f32_e32 v24, v1
	v_mul_f32_e32 v1, 0xbfb8aa3b, v19
	v_exp_f32_e32 v1, v1
	v_pk_fma_f32 v[22:23], v[70:71], v[2:3], v[138:139] op_sel_hi:[1,0,1]
	v_cvt_pk_bf16_f32 v20, v20, v21
	v_add_f32_e32 v1, 1.0, v1
	v_rcp_f32_e32 v25, v1
	s_nop 0
	v_pk_mul_f32 v[18:19], v[24:25], v[18:19]
	s_nop 0
	v_pk_mul_f32 v[18:19], v[22:23], v[18:19]
	s_nop 0
	v_cvt_pk_bf16_f32 v21, v18, v19
	global_store_dwordx2 v[6:7], v[20:21], off offset:1552
	s_waitcnt vmcnt(7)
	v_lshlrev_b32_e32 v20, 16, v16
	v_mul_f32_e32 v1, 0xbfb8aa3b, v20
	v_exp_f32_e32 v1, v1
	v_and_b32_e32 v21, 0xffff0000, v16
	v_lshlrev_b32_e32 v16, 16, v17
	v_and_b32_e32 v17, 0xffff0000, v17
	v_add_f32_e32 v1, 1.0, v1
	v_rcp_f32_e32 v22, v1
	v_mul_f32_e32 v1, 0xbfb8aa3b, v21
	v_exp_f32_e32 v1, v1
	v_pk_fma_f32 v[18:19], v[72:73], v[2:3], v[136:137] op_sel_hi:[1,0,1]
	v_add_f32_e32 v1, 1.0, v1
	v_rcp_f32_e32 v23, v1
	v_mul_f32_e32 v1, 0xbfb8aa3b, v16
	v_exp_f32_e32 v1, v1
	v_pk_mul_f32 v[20:21], v[22:23], v[20:21]
	s_nop 0
	v_pk_mul_f32 v[18:19], v[18:19], v[20:21]
	v_add_f32_e32 v1, 1.0, v1
	v_rcp_f32_e32 v22, v1
	v_mul_f32_e32 v1, 0xbfb8aa3b, v17
	v_exp_f32_e32 v1, v1
	v_pk_fma_f32 v[20:21], v[74:75], v[2:3], v[134:135] op_sel_hi:[1,0,1]
	v_cvt_pk_bf16_f32 v18, v18, v19
	v_add_f32_e32 v1, 1.0, v1
	v_rcp_f32_e32 v23, v1
	s_nop 0
	v_pk_mul_f32 v[16:17], v[22:23], v[16:17]
	s_nop 0
	v_pk_mul_f32 v[16:17], v[20:21], v[16:17]
	s_nop 0
	v_cvt_pk_bf16_f32 v19, v16, v17
	global_store_dwordx2 v[6:7], v[18:19], off offset:1568
	s_waitcnt vmcnt(7)
	v_lshlrev_b32_e32 v18, 16, v14
	v_mul_f32_e32 v1, 0xbfb8aa3b, v18
	v_exp_f32_e32 v1, v1
	v_and_b32_e32 v19, 0xffff0000, v14
	v_lshlrev_b32_e32 v14, 16, v15
	v_and_b32_e32 v15, 0xffff0000, v15
	v_add_f32_e32 v1, 1.0, v1
	v_rcp_f32_e32 v20, v1
	v_mul_f32_e32 v1, 0xbfb8aa3b, v19
	v_exp_f32_e32 v1, v1
	v_pk_fma_f32 v[16:17], v[76:77], v[2:3], v[132:133] op_sel_hi:[1,0,1]
	v_add_f32_e32 v1, 1.0, v1
	v_rcp_f32_e32 v21, v1
	v_mul_f32_e32 v1, 0xbfb8aa3b, v14
	v_exp_f32_e32 v1, v1
	v_pk_mul_f32 v[18:19], v[20:21], v[18:19]
	s_nop 0
	v_pk_mul_f32 v[16:17], v[16:17], v[18:19]
	v_add_f32_e32 v1, 1.0, v1
	v_rcp_f32_e32 v20, v1
	v_mul_f32_e32 v1, 0xbfb8aa3b, v15
	v_exp_f32_e32 v1, v1
	v_pk_fma_f32 v[18:19], v[78:79], v[2:3], v[130:131] op_sel_hi:[1,0,1]
	v_cvt_pk_bf16_f32 v16, v16, v17
	v_add_f32_e32 v1, 1.0, v1
	v_rcp_f32_e32 v21, v1
	s_nop 0
	v_pk_mul_f32 v[14:15], v[20:21], v[14:15]
	s_nop 0
	v_pk_mul_f32 v[14:15], v[18:19], v[14:15]
	s_nop 0
	v_cvt_pk_bf16_f32 v17, v14, v15
	global_store_dwordx2 v[6:7], v[16:17], off offset:1584
	s_waitcnt vmcnt(7)
	v_lshlrev_b32_e32 v16, 16, v12
	v_mul_f32_e32 v1, 0xbfb8aa3b, v16
	v_exp_f32_e32 v1, v1
	v_and_b32_e32 v17, 0xffff0000, v12
	v_lshlrev_b32_e32 v12, 16, v13
	v_and_b32_e32 v13, 0xffff0000, v13
	v_add_f32_e32 v1, 1.0, v1
	v_rcp_f32_e32 v18, v1
	v_mul_f32_e32 v1, 0xbfb8aa3b, v17
	v_exp_f32_e32 v1, v1
	v_pk_fma_f32 v[14:15], v[48:49], v[2:3], v[128:129] op_sel_hi:[1,0,1]
	v_add_f32_e32 v1, 1.0, v1
	v_rcp_f32_e32 v19, v1
	v_mul_f32_e32 v1, 0xbfb8aa3b, v12
	v_exp_f32_e32 v1, v1
	v_pk_mul_f32 v[16:17], v[18:19], v[16:17]
	s_nop 0
	v_pk_mul_f32 v[14:15], v[14:15], v[16:17]
	v_add_f32_e32 v1, 1.0, v1
	v_rcp_f32_e32 v18, v1
	v_mul_f32_e32 v1, 0xbfb8aa3b, v13
	v_exp_f32_e32 v1, v1
	v_pk_fma_f32 v[16:17], v[50:51], v[2:3], v[126:127] op_sel_hi:[1,0,1]
	v_cvt_pk_bf16_f32 v14, v14, v15
	v_add_f32_e32 v1, 1.0, v1
	v_rcp_f32_e32 v19, v1
	s_nop 0
	v_pk_mul_f32 v[12:13], v[18:19], v[12:13]
	s_nop 0
	v_pk_mul_f32 v[12:13], v[16:17], v[12:13]
	s_nop 0
	v_cvt_pk_bf16_f32 v15, v12, v13
	global_store_dwordx2 v[6:7], v[14:15], off offset:1600
	s_waitcnt vmcnt(7)
	v_lshlrev_b32_e32 v14, 16, v10
	v_mul_f32_e32 v1, 0xbfb8aa3b, v14
	v_exp_f32_e32 v1, v1
	v_and_b32_e32 v15, 0xffff0000, v10
	v_lshlrev_b32_e32 v10, 16, v11
	v_and_b32_e32 v11, 0xffff0000, v11
	v_add_f32_e32 v1, 1.0, v1
	v_rcp_f32_e32 v16, v1
	v_mul_f32_e32 v1, 0xbfb8aa3b, v15
	v_exp_f32_e32 v1, v1
	v_pk_fma_f32 v[12:13], v[52:53], v[2:3], v[124:125] op_sel_hi:[1,0,1]
	v_add_f32_e32 v1, 1.0, v1
	v_rcp_f32_e32 v17, v1
	v_mul_f32_e32 v1, 0xbfb8aa3b, v10
	v_exp_f32_e32 v1, v1
	v_pk_mul_f32 v[14:15], v[16:17], v[14:15]
	s_nop 0
	v_pk_mul_f32 v[12:13], v[12:13], v[14:15]
	v_add_f32_e32 v1, 1.0, v1
	v_rcp_f32_e32 v16, v1
	v_mul_f32_e32 v1, 0xbfb8aa3b, v11
	v_exp_f32_e32 v1, v1
	v_pk_fma_f32 v[14:15], v[54:55], v[2:3], v[122:123] op_sel_hi:[1,0,1]
	v_cvt_pk_bf16_f32 v12, v12, v13
	v_add_f32_e32 v1, 1.0, v1
	v_rcp_f32_e32 v17, v1
	s_nop 0
	v_pk_mul_f32 v[10:11], v[16:17], v[10:11]
	s_nop 0
	v_pk_mul_f32 v[10:11], v[14:15], v[10:11]
	s_nop 0
	v_cvt_pk_bf16_f32 v13, v10, v11
	global_store_dwordx2 v[6:7], v[12:13], off offset:1616
	s_waitcnt vmcnt(7)
	v_lshlrev_b32_e32 v12, 16, v8
	v_mul_f32_e32 v1, 0xbfb8aa3b, v12
	v_exp_f32_e32 v1, v1
	v_and_b32_e32 v13, 0xffff0000, v8
	v_lshlrev_b32_e32 v8, 16, v9
	v_and_b32_e32 v9, 0xffff0000, v9
	v_add_f32_e32 v1, 1.0, v1
	v_rcp_f32_e32 v14, v1
	v_mul_f32_e32 v1, 0xbfb8aa3b, v13
	v_exp_f32_e32 v1, v1
	v_pk_fma_f32 v[10:11], v[56:57], v[2:3], v[120:121] op_sel_hi:[1,0,1]
	v_add_f32_e32 v1, 1.0, v1
	v_rcp_f32_e32 v15, v1
	v_mul_f32_e32 v1, 0xbfb8aa3b, v8
	v_exp_f32_e32 v1, v1
	v_pk_mul_f32 v[12:13], v[14:15], v[12:13]
	s_nop 0
	v_pk_mul_f32 v[10:11], v[10:11], v[12:13]
	v_add_f32_e32 v1, 1.0, v1
	v_rcp_f32_e32 v14, v1
	v_mul_f32_e32 v1, 0xbfb8aa3b, v9
	v_exp_f32_e32 v1, v1
	v_pk_fma_f32 v[12:13], v[58:59], v[2:3], v[118:119] op_sel_hi:[1,0,1]
	v_cvt_pk_bf16_f32 v10, v10, v11
	v_add_f32_e32 v1, 1.0, v1
	v_rcp_f32_e32 v15, v1
	s_nop 0
	v_pk_mul_f32 v[8:9], v[14:15], v[8:9]
	s_nop 0
	v_pk_mul_f32 v[8:9], v[12:13], v[8:9]
	s_nop 0
	v_cvt_pk_bf16_f32 v11, v8, v9
	global_store_dwordx2 v[6:7], v[10:11], off offset:1632
	s_waitcnt vmcnt(7)
	v_lshlrev_b32_e32 v10, 16, v4
	v_mul_f32_e32 v1, 0xbfb8aa3b, v10
	v_exp_f32_e32 v1, v1
	v_and_b32_e32 v11, 0xffff0000, v4
	v_lshlrev_b32_e32 v4, 16, v5
	v_pk_fma_f32 v[8:9], v[60:61], v[2:3], v[116:117] op_sel_hi:[1,0,1]
	v_add_f32_e32 v1, 1.0, v1
	v_rcp_f32_e32 v12, v1
	v_mul_f32_e32 v1, 0xbfb8aa3b, v11
	v_exp_f32_e32 v1, v1
	v_and_b32_e32 v5, 0xffff0000, v5
	v_pk_fma_f32 v[2:3], v[62:63], v[2:3], v[114:115] op_sel_hi:[1,0,1]
	v_add_f32_e32 v1, 1.0, v1
	v_rcp_f32_e32 v13, v1
	v_mul_f32_e32 v1, 0xbfb8aa3b, v4
	v_exp_f32_e32 v1, v1
	v_pk_mul_f32 v[10:11], v[12:13], v[10:11]
	s_nop 0
	v_pk_mul_f32 v[8:9], v[8:9], v[10:11]
	v_add_f32_e32 v1, 1.0, v1
	v_rcp_f32_e32 v10, v1
	v_mul_f32_e32 v1, 0xbfb8aa3b, v5
	v_exp_f32_e32 v1, v1
	s_nop 0
	v_add_f32_e32 v1, 1.0, v1
	v_rcp_f32_e32 v11, v1
	s_nop 0
	v_pk_mul_f32 v[4:5], v[10:11], v[4:5]
	s_nop 0
	v_pk_mul_f32 v[2:3], v[2:3], v[4:5]
	v_cvt_pk_bf16_f32 v4, v8, v9
	v_cvt_pk_bf16_f32 v5, v2, v3
	global_store_dwordx2 v[6:7], v[4:5], off offset:1648
	s_barrier
